# P3 state update: the two independent 4-MFMA chains interleaved, shared k~ operand read once, operands read one step ahead, decay scaling of one chain under the other's tail
# speedup vs baseline: 1.0037x; 1.0004x over previous
.LBB0_440:
	v_add_u32_e32 v122, s52, v74
	v_add_u32_e32 v140, s45, v122
	v_add_u32_e32 v122, s46, v122
	v_add_u32_e32 v148, s44, v103
	v_add_u32_e32 v148, 0x27000, v148
	ds_read_b64_tr_b16 v[128:129], v121
	ds_read_b64_tr_b16 v[130:131], v121 offset:512
	ds_read_b64_tr_b16 v[124:125], v140 offset:32768
	ds_read_b64_tr_b16 v[126:127], v140 offset:33280
	ds_read_b64_tr_b16 v[150:151], v122 offset:32768
	ds_read_b64_tr_b16 v[152:153], v122 offset:33280
	ds_read_b64_tr_b16 v[132:133], v121 offset:1024
	ds_read_b64_tr_b16 v[134:135], v121 offset:1536
	ds_read_b64_tr_b16 v[136:137], v140 offset:33792
	ds_read_b64_tr_b16 v[138:139], v140 offset:34304
	ds_read_b64_tr_b16 v[154:155], v122 offset:33792
	ds_read_b64_tr_b16 v[156:157], v122 offset:34304
	s_waitcnt lgkmcnt(8)
	v_mfma_f32_32x32x16_bf16 v[2:17], v[124:127], v[128:131], v[2:17]
	s_waitcnt lgkmcnt(6)
	v_mfma_f32_32x32x16_bf16 v[18:33], v[150:153], v[128:131], v[18:33]
	ds_read_b64_tr_b16 v[158:159], v121 offset:2048
	ds_read_b64_tr_b16 v[160:161], v121 offset:2560
	ds_read_b64_tr_b16 v[162:163], v140 offset:34816
	ds_read_b64_tr_b16 v[164:165], v140 offset:35328
	ds_read_b64_tr_b16 v[166:167], v122 offset:34816
	ds_read_b64_tr_b16 v[168:169], v122 offset:35328
	s_waitcnt lgkmcnt(8)
	v_mfma_f32_32x32x16_bf16 v[2:17], v[136:139], v[132:135], v[2:17]
	s_waitcnt lgkmcnt(6)
	v_mfma_f32_32x32x16_bf16 v[18:33], v[154:157], v[132:135], v[18:33]
	ds_read_b64_tr_b16 v[170:171], v121 offset:3072
	ds_read_b64_tr_b16 v[172:173], v121 offset:3584
	ds_read_b64_tr_b16 v[174:175], v140 offset:35840
	ds_read_b64_tr_b16 v[176:177], v140 offset:36352
	ds_read_b64_tr_b16 v[178:179], v122 offset:35840
	ds_read_b64_tr_b16 v[180:181], v122 offset:36352
	s_waitcnt lgkmcnt(8)
	v_mfma_f32_32x32x16_bf16 v[2:17], v[162:165], v[158:161], v[2:17]
	s_waitcnt lgkmcnt(6)
	v_mfma_f32_32x32x16_bf16 v[18:33], v[166:169], v[158:161], v[18:33]
	ds_read_b128 v[124:127], v148
	ds_read_b128 v[128:131], v148 offset:32
	ds_read_b128 v[132:135], v148 offset:64
	ds_read_b128 v[136:139], v148 offset:96
	ds_read_b128 v[182:185], v148 offset:128
	ds_read_b128 v[186:189], v148 offset:160
	ds_read_b128 v[190:193], v148 offset:192
	ds_read_b128 v[194:197], v148 offset:224
	s_waitcnt lgkmcnt(10)
	v_mfma_f32_32x32x16_bf16 v[2:17], v[174:177], v[170:173], v[2:17]
	s_waitcnt lgkmcnt(8)
	v_mfma_f32_32x32x16_bf16 v[18:33], v[178:181], v[170:173], v[18:33]
	s_waitcnt lgkmcnt(4)
	s_nop 10
	v_pk_mul_f32 v[2:3], v[2:3], v[124:125]
	v_pk_mul_f32 v[4:5], v[4:5], v[126:127]
	v_pk_mul_f32 v[6:7], v[6:7], v[128:129]
	v_pk_mul_f32 v[8:9], v[8:9], v[130:131]
	v_pk_mul_f32 v[10:11], v[10:11], v[132:133]
	v_pk_mul_f32 v[12:13], v[12:13], v[134:135]
	v_pk_mul_f32 v[14:15], v[14:15], v[136:137]
	v_pk_mul_f32 v[16:17], v[16:17], v[138:139]
	v_cvt_pk_bf16_f32 v140, v2, v3
	v_cvt_pk_bf16_f32 v141, v4, v5
	v_cvt_pk_bf16_f32 v142, v6, v7
	v_cvt_pk_bf16_f32 v143, v8, v9
	v_cvt_pk_bf16_f32 v144, v10, v11
	v_cvt_pk_bf16_f32 v145, v12, v13
	v_cvt_pk_bf16_f32 v146, v14, v15
	v_cvt_pk_bf16_f32 v147, v16, v17
	ds_write_b64 v110, v[140:141]
	ds_write_b64 v111, v[142:143]
	ds_write_b64 v112, v[144:145]
	ds_write_b64 v113, v[146:147]
	s_waitcnt lgkmcnt(4)
	v_pk_mul_f32 v[18:19], v[18:19], v[182:183]
	v_pk_mul_f32 v[20:21], v[20:21], v[184:185]
	v_pk_mul_f32 v[22:23], v[22:23], v[186:187]
	v_pk_mul_f32 v[24:25], v[24:25], v[188:189]
	v_pk_mul_f32 v[26:27], v[26:27], v[190:191]
	v_pk_mul_f32 v[28:29], v[28:29], v[192:193]
	v_pk_mul_f32 v[30:31], v[30:31], v[194:195]
	v_pk_mul_f32 v[32:33], v[32:33], v[196:197]
	v_cvt_pk_bf16_f32 v150, v18, v19
	v_cvt_pk_bf16_f32 v151, v20, v21
	v_cvt_pk_bf16_f32 v152, v22, v23
	v_cvt_pk_bf16_f32 v153, v24, v25
	v_cvt_pk_bf16_f32 v154, v26, v27
	v_cvt_pk_bf16_f32 v155, v28, v29
	v_cvt_pk_bf16_f32 v156, v30, v31
	v_cvt_pk_bf16_f32 v157, v32, v33
	ds_write_b64 v114, v[150:151]
	ds_write_b64 v115, v[152:153]
	ds_write_b64 v116, v[154:155]
	ds_write_b64 v117, v[156:157]
